# weight conversion batches <3> and <6,10,7>: gains to own registers, multiplies deferred to the consumer (loop header); masked tiles use a 1.0 preset
# baseline (speedup 1.0000x reference)
.LBB0_598:
	s_cmp_eq_u32 s26, 0
	s_cbranch_scc1 .LBB0_805
	s_abs_i32 s0, s27
	v_cvt_f32_u32_e32 v0, s0
	s_sub_i32 s1, 0, s0
	v_rcp_iflag_f32_e32 v0, v0
	s_nop 0
	v_mul_f32_e32 v0, 0x4f7ffffe, v0
	v_cvt_u32_f32_e32 v0, v0
	s_nop 0
	v_readfirstlane_b32 s4, v0
	s_mul_i32 s1, s1, s4
	s_mul_hi_u32 s1, s4, s1
	s_add_i32 s4, s4, s1
	s_mul_hi_u32 s1, s4, 0x580
	s_mul_i32 s1, s1, s0
	s_sub_i32 s1, 0x580, s1
	s_sub_i32 s4, s1, s0
	s_cmp_ge_u32 s1, s0
	s_cselect_b32 s1, s4, s1
	s_sub_i32 s4, s1, s0
	s_cmp_ge_u32 s1, s0
	s_cselect_b32 s0, s4, s1
	s_cmp_eq_u32 s0, 0
	s_cselect_b64 s[4:5], -1, 0
	s_cmp_lt_i32 s66, s0
	s_cselect_b64 s[6:7], -1, 0
	s_or_b64 s[4:5], s[4:5], s[6:7]
	s_and_b64 vcc, exec, s[4:5]
	s_cbranch_vccnz .LBB0_805
	s_sub_i32 s20, s66, s0
	s_sub_i32 s44, s27, s0
	s_cmp_lt_i32 s26, 2
	s_mov_b64 s[0:1], -1
	s_cbranch_scc1 .LBB0_774
	s_cmp_lt_i32 s26, 3
	s_cbranch_scc1 .LBB0_721
	s_cmp_lg_u32 s26, 3
	s_cbranch_scc0 .LBB0_609
	v_mov_b32_e32 v19, v173
	s_cmpk_gt_i32 s20, 0x2bf
	s_movk_i32 s22, 0x5800
	s_cbranch_scc1 .LBB0_608
	v_readlane_b32 s0, v254, 34
	v_readlane_b32 s1, v254, 35
	s_add_u32 s0, s0, 0x4200000
	s_addc_u32 s1, s1, 0
	v_readlane_b32 s4, v254, 32
	v_readlane_b32 s5, v254, 33
	s_add_u32 s4, s4, 0x3000
	s_addc_u32 s5, s5, 0
	v_readlane_b32 s6, v254, 48
	s_sext_i32_i16 s8, s20
	v_readlane_b32 s7, v254, 49
	s_add_u32 s6, s6, 0x2100000
	s_mulk_i32 s8, 0xba3
	s_addc_u32 s7, s7, 0
	s_lshr_b32 s9, s8, 31
	s_ashr_i32 s8, s8, 17
	s_add_i32 s9, s8, s9
	s_lshl_b32 s8, s9, 6
	s_mul_i32 s9, s9, 44
	s_sub_i32 s10, s20, s9
	s_sext_i32_i16 s11, s10
	s_lshl_b32 s9, s11, 7
	s_bfe_i32 s10, s10, 0x10000
	s_lshl_b32 s11, s11, 6
	v_lshlrev_b32_e32 v0, 2, v19
	s_and_b32 s10, s10, 0xb00
	s_and_b32 s11, s11, 0xffffff80
	v_and_b32_e32 v20, 64, v0
	s_add_i32 s10, s10, s11
	v_and_b32_e32 v18, 60, v0
	v_ashrrev_i32_e32 v21, 5, v19
	v_or_b32_e32 v0, s10, v20
	v_add_u32_e32 v8, s8, v21
	v_mov_b64_e32 v[16:17], s[0:1]
	v_ashrrev_i32_e32 v1, 31, v0
	v_mad_i64_i32 v[4:5], s[10:11], v8, s22, v[16:17]
	v_lshlrev_b64 v[26:27], 2, v[0:1]
	v_lshl_add_u64 v[0:1], v[4:5], 0, v[26:27]
	v_lshlrev_b32_e32 v2, 2, v18
	v_ashrrev_i32_e32 v9, 31, v8
	v_lshl_add_u64 v[0:1], v[0:1], 0, v[2:3]
	global_load_dwordx4 v[42:45], v[0:1], off
	v_lshl_add_u64 v[0:1], v[8:9], 2, s[4:5]
	global_load_dword v58, v[0:1], off
	s_lshl_b32 s12, s44, 7
	s_lshl_b32 s14, s44, 6
	v_lshlrev_b32_e32 v18, 2, v18
	s_mov_b32 s15, s20
	s_mov_b32 s16, s9
	v_add_u32_e32 v6, 0x200, v19
	v_ashrrev_i32_e32 v22, 5, v6
	v_add_u32_e32 v6, s8, v22
	v_mad_i64_i32 v[8:9], s[10:11], v6, s22, v[16:17]
	v_ashrrev_i32_e32 v7, 31, v6
	v_lshl_add_u64 v[8:9], v[8:9], 0, v[26:27]
	v_lshl_add_u64 v[8:9], v[8:9], 0, v[2:3]
	v_lshl_add_u64 v[6:7], v[6:7], 2, s[4:5]
	global_load_dwordx4 v[46:49], v[8:9], off
	s_nop 0
	global_load_dword v60, v[6:7], off
	v_add_u32_e32 v10, 0x400, v19
	v_ashrrev_i32_e32 v23, 5, v10
	v_add_u32_e32 v10, s8, v23
	v_mad_i64_i32 v[12:13], s[10:11], v10, s22, v[16:17]
	v_ashrrev_i32_e32 v11, 31, v10
	v_lshl_add_u64 v[12:13], v[12:13], 0, v[26:27]
	v_lshl_add_u64 v[12:13], v[12:13], 0, v[2:3]
	v_lshl_add_u64 v[10:11], v[10:11], 2, s[4:5]
	global_load_dwordx4 v[50:53], v[12:13], off
	s_nop 0
	global_load_dword v62, v[10:11], off
	v_add_u32_e32 v14, 0x600, v19
	v_ashrrev_i32_e32 v24, 5, v14
	v_add_u32_e32 v14, s8, v24
	v_mad_i64_i32 v[16:17], s[10:11], v14, s22, v[16:17]
	v_ashrrev_i32_e32 v15, 31, v14
	v_lshl_add_u64 v[16:17], v[16:17], 0, v[26:27]
	v_lshl_add_u64 v[16:17], v[16:17], 0, v[2:3]
	v_lshl_add_u64 v[14:15], v[14:15], 2, s[4:5]
	global_load_dwordx4 v[54:57], v[16:17], off
	global_load_dword v64, v[14:15], off
	s_movk_i32 s10, 0x204
	v_mul_lo_u32 v31, v24, s10
	v_lshlrev_b32_e32 v2, 4, v19
	v_and_b32_e32 v25, 0x1f0, v2
	v_and_b32_e32 v2, 48, v2
	v_add_u32_e32 v30, 0, v25
	v_ashrrev_i32_e32 v25, 2, v19
	v_mul_u32_u24_e32 v26, 0x204, v2
	v_and_b32_e32 v19, -4, v19
	v_add3_u32 v26, 0, v26, v19
	v_mul_lo_u32 v19, v21, s10
	v_mul_lo_u32 v28, v22, s10
	v_mul_lo_u32 v29, v23, s10
	s_add_i32 s10, s20, s44
	s_lshl_b32 s11, s10, 7
	s_lshl_b32 s13, s10, 6
	v_add_u32_e32 v27, v30, v19
	v_add_u32_e32 v28, v30, v28
	v_add_u32_e32 v29, v30, v29
	v_add_u32_e32 v30, v30, v31
	v_lshlrev_b32_e32 v2, 1, v2
	s_branch .LBB0_606

.LBB0_606:
	s_cmpk_gt_i32 s10, 0x2bf
	s_mov_b32 s17, s8
	s_waitcnt vmcnt(0)
	v_pk_mul_f32 v[0:1], v[44:45], v[58:59] op_sel_hi:[1,0]
	v_pk_mul_f32 v[4:5], v[42:43], v[58:59] op_sel_hi:[1,0]
	v_pk_mul_f32 v[6:7], v[48:49], v[60:61] op_sel_hi:[1,0]
	v_pk_mul_f32 v[8:9], v[46:47], v[60:61] op_sel_hi:[1,0]
	v_pk_mul_f32 v[10:11], v[52:53], v[62:63] op_sel_hi:[1,0]
	v_pk_mul_f32 v[12:13], v[50:51], v[62:63] op_sel_hi:[1,0]
	v_pk_mul_f32 v[14:15], v[56:57], v[64:65] op_sel_hi:[1,0]
	v_pk_mul_f32 v[16:17], v[54:55], v[64:65] op_sel_hi:[1,0]
	ds_write2_b32 v27, v4, v5 offset1:1
	ds_write2_b32 v27, v0, v1 offset0:2 offset1:3
	ds_write2_b32 v28, v8, v9 offset1:1
	ds_write2_b32 v28, v6, v7 offset0:2 offset1:3
	ds_write2_b32 v29, v12, v13 offset1:1
	ds_write2_b32 v29, v10, v11 offset0:2 offset1:3
	ds_write2_b32 v30, v16, v17 offset1:1
	ds_write2_b32 v30, v14, v15 offset0:2 offset1:3
	s_cbranch_scc1 .LBB0_605
	s_mul_hi_i32 s16, s10, 0x2e8ba2e9
	s_lshr_b32 s17, s16, 31
	s_ashr_i32 s16, s16, 3
	s_add_i32 s18, s16, s17
	s_lshl_b32 s17, s18, 6
	s_mul_i32 s16, s18, 0xffffea00
	s_mulk_i32 s18, 0xf500
	s_bfe_i32 s19, s10, 0x10000
	s_add_i32 s18, s13, s18
	s_and_b32 s19, s19, 0xb00
	s_and_b32 s18, s18, 0xffffff80
	s_add_i32 s19, s19, s18
	v_or_b32_e32 v0, s19, v20
	v_add_u32_e32 v8, s17, v21
	v_mov_b64_e32 v[16:17], s[0:1]
	v_ashrrev_i32_e32 v1, 31, v0
	v_mad_i64_i32 v[4:5], s[18:19], v8, s22, v[16:17]
	v_lshlrev_b64 v[32:33], 2, v[0:1]
	v_lshl_add_u64 v[0:1], v[4:5], 0, v[32:33]
	v_mov_b32_e32 v19, v3
	v_ashrrev_i32_e32 v9, 31, v8
	v_lshl_add_u64 v[0:1], v[0:1], 0, v[18:19]
	global_load_dwordx4 v[42:45], v[0:1], off
	v_lshl_add_u64 v[0:1], v[8:9], 2, s[4:5]
	global_load_dword v58, v[0:1], off
	s_add_i32 s16, s11, s16
	v_add_u32_e32 v6, s17, v22
	v_mad_i64_i32 v[8:9], s[18:19], v6, s22, v[16:17]
	v_ashrrev_i32_e32 v7, 31, v6
	v_lshl_add_u64 v[8:9], v[8:9], 0, v[32:33]
	v_lshl_add_u64 v[8:9], v[8:9], 0, v[18:19]
	v_lshl_add_u64 v[6:7], v[6:7], 2, s[4:5]
	global_load_dwordx4 v[46:49], v[8:9], off
	s_nop 0
	global_load_dword v60, v[6:7], off
	v_add_u32_e32 v10, s17, v23
	v_mad_i64_i32 v[12:13], s[18:19], v10, s22, v[16:17]
	v_ashrrev_i32_e32 v11, 31, v10
	v_lshl_add_u64 v[12:13], v[12:13], 0, v[32:33]
	v_lshl_add_u64 v[12:13], v[12:13], 0, v[18:19]
	v_lshl_add_u64 v[10:11], v[10:11], 2, s[4:5]
	global_load_dwordx4 v[50:53], v[12:13], off
	s_nop 0
	global_load_dword v62, v[10:11], off
	v_add_u32_e32 v14, s17, v24
	v_mad_i64_i32 v[16:17], s[18:19], v14, s22, v[16:17]
	v_ashrrev_i32_e32 v15, 31, v14
	v_lshl_add_u64 v[16:17], v[16:17], 0, v[32:33]
	v_lshl_add_u64 v[16:17], v[16:17], 0, v[18:19]
	v_lshl_add_u64 v[14:15], v[14:15], 2, s[4:5]
	global_load_dwordx4 v[54:57], v[16:17], off
	s_nop 0
	global_load_dword v64, v[14:15], off
	s_branch .LBB0_605

.LBB0_626:
	s_or_b64 exec, exec, s[18:19]
	v_mov_b32_e32 v242, 1.0
	v_mov_b32_e32 v244, 1.0
	v_mov_b32_e32 v246, 1.0
	v_mov_b32_e32 v248, 1.0
	v_mov_b32_e32 v4, 0
	v_ashrrev_i32_e32 v26, 5, v22
	v_mov_b32_e32 v5, v4
	v_mov_b32_e32 v6, v4
	v_mov_b32_e32 v7, v4
	s_and_saveexec_b64 s[18:19], s[22:23]
	s_cbranch_execz .LBB0_631
	v_mov_b32_e32 v7, 0
	v_mov_b32_e32 v6, 0
	v_mov_b32_e32 v5, 0
	v_mov_b32_e32 v4, 0
	s_and_saveexec_b64 s[22:23], s[24:25]
	s_cbranch_execz .LBB0_630
	v_add_u32_e32 v10, s8, v26
	v_ashrrev_i32_e32 v11, 31, v10
	v_mul_lo_u32 v1, s14, v11
	v_mul_lo_u32 v2, s15, v10
	v_mad_u64_u32 v[4:5], s[24:25], s14, v10, 0
	v_add3_u32 v5, v5, v1, v2
	v_lshl_add_u64 v[4:5], v[4:5], 2, s[10:11]
	v_ashrrev_i32_e32 v9, 31, v8
	v_lshl_add_u64 v[4:5], v[8:9], 2, v[4:5]
	v_lshlrev_b32_e32 v2, 2, v24
	v_lshl_add_u64 v[4:5], v[4:5], 0, v[2:3]
	global_load_dwordx4 v[4:7], v[4:5], off
	s_cmp_eq_u64 s[12:13], 0
	s_cbranch_scc1 .LBB0_630
	v_lshl_add_u64 v[8:9], v[10:11], 2, s[12:13]
	global_load_dword v242, v[8:9], off

.LBB0_637:
	s_or_b64 exec, exec, s[18:19]
	v_add_u32_e32 v1, 0x200, v22
	v_mov_b32_e32 v8, 0
	v_ashrrev_i32_e32 v27, 5, v1
	v_mov_b32_e32 v9, v8
	v_mov_b32_e32 v10, v8
	v_mov_b32_e32 v11, v8
	s_and_saveexec_b64 s[18:19], s[22:23]
	s_cbranch_execz .LBB0_642
	v_mov_b32_e32 v11, 0
	v_mov_b32_e32 v10, 0
	v_mov_b32_e32 v9, 0
	v_mov_b32_e32 v8, 0
	s_and_saveexec_b64 s[22:23], s[24:25]
	s_cbranch_execz .LBB0_641
	v_add_u32_e32 v14, s8, v27
	v_ashrrev_i32_e32 v15, 31, v14
	v_mul_lo_u32 v1, s14, v15
	v_mul_lo_u32 v2, s15, v14
	v_mad_u64_u32 v[8:9], s[24:25], s14, v14, 0
	v_add3_u32 v9, v9, v1, v2
	v_lshl_add_u64 v[8:9], v[8:9], 2, s[10:11]
	v_ashrrev_i32_e32 v13, 31, v12
	v_lshl_add_u64 v[8:9], v[12:13], 2, v[8:9]
	v_lshlrev_b32_e32 v2, 2, v24
	v_lshl_add_u64 v[8:9], v[8:9], 0, v[2:3]
	global_load_dwordx4 v[8:11], v[8:9], off
	s_cmp_eq_u64 s[12:13], 0
	s_cbranch_scc1 .LBB0_641
	v_lshl_add_u64 v[12:13], v[14:15], 2, s[12:13]
	global_load_dword v244, v[12:13], off

.LBB0_648:
	s_or_b64 exec, exec, s[18:19]
	v_add_u32_e32 v1, 0x400, v22
	v_mov_b32_e32 v12, 0
	v_ashrrev_i32_e32 v28, 5, v1
	v_mov_b32_e32 v13, v12
	v_mov_b32_e32 v14, v12
	v_mov_b32_e32 v15, v12
	s_and_saveexec_b64 s[18:19], s[22:23]
	s_cbranch_execz .LBB0_653
	v_mov_b32_e32 v15, 0
	v_mov_b32_e32 v14, 0
	v_mov_b32_e32 v13, 0
	v_mov_b32_e32 v12, 0
	s_and_saveexec_b64 s[22:23], s[24:25]
	s_cbranch_execz .LBB0_652
	v_add_u32_e32 v18, s8, v28
	v_ashrrev_i32_e32 v19, 31, v18
	v_mul_lo_u32 v1, s14, v19
	v_mul_lo_u32 v2, s15, v18
	v_mad_u64_u32 v[12:13], s[24:25], s14, v18, 0
	v_add3_u32 v13, v13, v1, v2
	v_lshl_add_u64 v[12:13], v[12:13], 2, s[10:11]
	v_ashrrev_i32_e32 v17, 31, v16
	v_lshl_add_u64 v[12:13], v[16:17], 2, v[12:13]
	v_lshlrev_b32_e32 v2, 2, v24
	v_lshl_add_u64 v[12:13], v[12:13], 0, v[2:3]
	global_load_dwordx4 v[12:15], v[12:13], off
	s_cmp_eq_u64 s[12:13], 0
	s_cbranch_scc1 .LBB0_652
	v_lshl_add_u64 v[16:17], v[18:19], 2, s[12:13]
	global_load_dword v246, v[16:17], off

.LBB0_659:
	s_or_b64 exec, exec, s[18:19]
	v_add_u32_e32 v1, 0x600, v22
	v_ashrrev_i32_e32 v29, 5, v1
	v_mov_b32_e32 v16, 0
	v_mov_b32_e32 v17, 0
	v_mov_b32_e32 v18, 0
	v_mov_b32_e32 v19, 0
	s_and_saveexec_b64 s[16:17], s[24:25]
	s_cbranch_execz .LBB0_664
	v_mov_b32_e32 v19, 0
	v_mov_b32_e32 v18, 0
	v_mov_b32_e32 v17, 0
	v_mov_b32_e32 v16, 0
	s_and_saveexec_b64 s[18:19], s[22:23]
	s_cbranch_execz .LBB0_663
	v_add_u32_e32 v20, s8, v29
	v_ashrrev_i32_e32 v21, 31, v20
	v_mul_lo_u32 v1, s14, v21
	v_mul_lo_u32 v2, s15, v20
	v_mad_u64_u32 v[16:17], s[14:15], s14, v20, 0
	v_add3_u32 v17, v17, v1, v2
	v_lshl_add_u64 v[16:17], v[16:17], 2, s[10:11]
	v_ashrrev_i32_e32 v1, 31, v0
	v_lshl_add_u64 v[0:1], v[0:1], 2, v[16:17]
	v_lshlrev_b32_e32 v2, 2, v24
	v_lshl_add_u64 v[0:1], v[0:1], 0, v[2:3]
	global_load_dwordx4 v[16:19], v[0:1], off
	s_cmp_eq_u64 s[12:13], 0
	s_cbranch_scc1 .LBB0_663
	v_lshl_add_u64 v[0:1], v[20:21], 2, s[12:13]
	global_load_dword v248, v[0:1], off

.LBB0_668:
	s_cmpk_gt_i32 s46, 0x49f
	s_mov_b32 s54, s8
	s_waitcnt vmcnt(0)
	v_pk_mul_f32 v[6:7], v[6:7], v[242:243] op_sel_hi:[1,0]
	v_pk_mul_f32 v[4:5], v[4:5], v[242:243] op_sel_hi:[1,0]
	v_pk_mul_f32 v[10:11], v[10:11], v[244:245] op_sel_hi:[1,0]
	v_pk_mul_f32 v[8:9], v[8:9], v[244:245] op_sel_hi:[1,0]
	v_pk_mul_f32 v[14:15], v[14:15], v[246:247] op_sel_hi:[1,0]
	v_pk_mul_f32 v[12:13], v[12:13], v[246:247] op_sel_hi:[1,0]
	v_pk_mul_f32 v[18:19], v[18:19], v[248:249] op_sel_hi:[1,0]
	v_pk_mul_f32 v[16:17], v[16:17], v[248:249] op_sel_hi:[1,0]
	v_mov_b32_e32 v242, 1.0
	v_mov_b32_e32 v244, 1.0
	v_mov_b32_e32 v246, 1.0
	v_mov_b32_e32 v248, 1.0
	ds_write2_b32 v32, v4, v5 offset1:1
	ds_write2_b32 v32, v6, v7 offset0:2 offset1:3
	ds_write2_b32 v33, v8, v9 offset1:1
	ds_write2_b32 v33, v10, v11 offset0:2 offset1:3
	ds_write2_b32 v34, v12, v13 offset1:1
	ds_write2_b32 v34, v14, v15 offset0:2 offset1:3
	ds_write2_b32 v35, v16, v17 offset1:1
	ds_write2_b32 v35, v18, v19 offset0:2 offset1:3
	s_cbranch_scc1 .LBB0_667
	s_cmpk_gt_i32 s46, 0x15f
	s_mov_b64 s[36:37], -1
	s_cbranch_scc0 .LBB0_674
	s_mov_b64 s[30:31], -1
	s_cmpk_gt_u32 s46, 0x33f
	s_mov_b64 s[24:25], -1
	s_cbranch_scc0 .LBB0_672
	s_and_b32 s54, s49, 0x7ffc0
	s_and_b32 s52, s47, 0x380
	s_mov_b64 s[24:25], 0

.LBB0_682:
	s_or_b64 exec, exec, s[36:37]
	v_mov_b32_e32 v4, 0
	v_mov_b32_e32 v5, 0
	v_mov_b32_e32 v6, 0
	v_mov_b32_e32 v7, 0
	s_and_saveexec_b64 s[36:37], s[38:39]
	s_cbranch_execz .LBB0_687
	v_mov_b32_e32 v7, 0
	v_mov_b32_e32 v6, 0
	v_mov_b32_e32 v5, 0
	v_mov_b32_e32 v4, 0
	s_and_saveexec_b64 s[38:39], s[40:41]
	s_cbranch_execz .LBB0_686
	v_add_u32_e32 v10, s54, v26
	v_ashrrev_i32_e32 v11, 31, v10
	v_mul_lo_u32 v1, s24, v11
	v_mul_lo_u32 v2, s25, v10
	v_mad_u64_u32 v[4:5], s[40:41], s24, v10, 0
	v_add3_u32 v5, v5, v1, v2
	v_lshl_add_u64 v[4:5], v[4:5], 2, s[28:29]
	v_ashrrev_i32_e32 v9, 31, v8
	v_lshl_add_u64 v[4:5], v[8:9], 2, v[4:5]
	v_lshlrev_b32_e32 v2, 2, v24
	v_lshl_add_u64 v[4:5], v[4:5], 0, v[2:3]
	global_load_dwordx4 v[4:7], v[4:5], off
	s_cmp_eq_u64 s[26:27], 0
	s_cbranch_scc1 .LBB0_686
	v_lshl_add_u64 v[8:9], v[10:11], 2, s[26:27]
	global_load_dword v242, v[8:9], off

.LBB0_693:
	s_or_b64 exec, exec, s[36:37]
	v_mov_b32_e32 v8, 0
	v_mov_b32_e32 v9, 0
	v_mov_b32_e32 v10, 0
	v_mov_b32_e32 v11, 0
	s_and_saveexec_b64 s[36:37], s[38:39]
	s_cbranch_execz .LBB0_698
	v_mov_b32_e32 v11, 0
	v_mov_b32_e32 v10, 0
	v_mov_b32_e32 v9, 0
	v_mov_b32_e32 v8, 0
	s_and_saveexec_b64 s[38:39], s[40:41]
	s_cbranch_execz .LBB0_697
	v_add_u32_e32 v14, s54, v27
	v_ashrrev_i32_e32 v15, 31, v14
	v_mul_lo_u32 v1, s24, v15
	v_mul_lo_u32 v2, s25, v14
	v_mad_u64_u32 v[8:9], s[40:41], s24, v14, 0
	v_add3_u32 v9, v9, v1, v2
	v_lshl_add_u64 v[8:9], v[8:9], 2, s[28:29]
	v_ashrrev_i32_e32 v13, 31, v12
	v_lshl_add_u64 v[8:9], v[12:13], 2, v[8:9]
	v_lshlrev_b32_e32 v2, 2, v24
	v_lshl_add_u64 v[8:9], v[8:9], 0, v[2:3]
	global_load_dwordx4 v[8:11], v[8:9], off
	s_cmp_eq_u64 s[26:27], 0
	s_cbranch_scc1 .LBB0_697
	v_lshl_add_u64 v[12:13], v[14:15], 2, s[26:27]
	global_load_dword v244, v[12:13], off

.LBB0_704:
	s_or_b64 exec, exec, s[36:37]
	v_mov_b32_e32 v12, 0
	v_mov_b32_e32 v13, 0
	v_mov_b32_e32 v14, 0
	v_mov_b32_e32 v15, 0
	s_and_saveexec_b64 s[36:37], s[38:39]
	s_cbranch_execz .LBB0_709
	v_mov_b32_e32 v15, 0
	v_mov_b32_e32 v14, 0
	v_mov_b32_e32 v13, 0
	v_mov_b32_e32 v12, 0
	s_and_saveexec_b64 s[38:39], s[40:41]
	s_cbranch_execz .LBB0_708
	v_add_u32_e32 v18, s54, v28
	v_ashrrev_i32_e32 v19, 31, v18
	v_mul_lo_u32 v1, s24, v19
	v_mul_lo_u32 v2, s25, v18
	v_mad_u64_u32 v[12:13], s[40:41], s24, v18, 0
	v_add3_u32 v13, v13, v1, v2
	v_lshl_add_u64 v[12:13], v[12:13], 2, s[28:29]
	v_ashrrev_i32_e32 v17, 31, v16
	v_lshl_add_u64 v[12:13], v[16:17], 2, v[12:13]
	v_lshlrev_b32_e32 v2, 2, v24
	v_lshl_add_u64 v[12:13], v[12:13], 0, v[2:3]
	global_load_dwordx4 v[12:15], v[12:13], off
	s_cmp_eq_u64 s[26:27], 0
	s_cbranch_scc1 .LBB0_708
	v_lshl_add_u64 v[16:17], v[18:19], 2, s[26:27]
	global_load_dword v246, v[16:17], off

.LBB0_715:
	s_or_b64 exec, exec, s[36:37]
	v_mov_b32_e32 v16, 0
	v_mov_b32_e32 v17, 0
	v_mov_b32_e32 v18, 0
	v_mov_b32_e32 v19, 0
	s_and_saveexec_b64 s[30:31], s[40:41]
	s_cbranch_execz .LBB0_666
	v_mov_b32_e32 v19, 0
	v_mov_b32_e32 v18, 0
	v_mov_b32_e32 v17, 0
	v_mov_b32_e32 v16, 0
	s_and_saveexec_b64 s[36:37], s[38:39]
	s_cbranch_execz .LBB0_665
	v_add_u32_e32 v22, s54, v29
	v_ashrrev_i32_e32 v23, 31, v22
	v_mul_lo_u32 v1, s24, v23
	v_mul_lo_u32 v2, s25, v22
	v_mad_u64_u32 v[16:17], s[24:25], s24, v22, 0
	v_add3_u32 v17, v17, v1, v2
	v_lshl_add_u64 v[16:17], v[16:17], 2, s[28:29]
	v_ashrrev_i32_e32 v21, 31, v20
	v_lshl_add_u64 v[16:17], v[20:21], 2, v[16:17]
	v_lshlrev_b32_e32 v2, 2, v24
	v_lshl_add_u64 v[16:17], v[16:17], 0, v[2:3]
	global_load_dwordx4 v[16:19], v[16:17], off
	s_cmp_eq_u64 s[26:27], 0
	s_cbranch_scc1 .LBB0_665
	v_lshl_add_u64 v[20:21], v[22:23], 2, s[26:27]
	global_load_dword v248, v[20:21], off
	s_branch .LBB0_665
